# added: grid-barrier non-leader workgroups poll the cross-XCD generation word directly (one release hop fewer per barrier)
# baseline (speedup 1.0000x reference)
.LBB0_253:
	s_or_b64 exec, exec, s[10:11]
	v_cvt_f32_u32_e32 v5, v3
	s_waitcnt vmcnt(0)
	v_readfirstlane_b32 s0, v4
	v_sub_u32_e32 v4, 0, v3
	v_rcp_iflag_f32_e32 v5, v5
	v_add_u32_e32 v6, s0, v0
	v_mul_f32_e32 v5, 0x4f7ffffe, v5
	v_cvt_u32_f32_e32 v5, v5
	v_mul_lo_u32 v0, v4, v5
	v_mul_hi_u32 v0, v5, v0
	v_add_u32_e32 v0, v5, v0
	v_mul_hi_u32 v0, v6, v0
	v_mul_lo_u32 v4, v0, v3
	v_sub_u32_e32 v4, v6, v4
	v_add_u32_e32 v5, 1, v0
	v_cmp_ge_u32_e32 vcc, v4, v3
	s_nop 1
	v_cndmask_b32_e32 v0, v0, v5, vcc
	v_sub_u32_e32 v5, v4, v3
	v_cndmask_b32_e32 v4, v4, v5, vcc
	v_add_u32_e32 v5, 1, v0
	v_cmp_ge_u32_e32 vcc, v4, v3
	v_add_u32_e32 v4, 1, v6
	s_nop 0
	v_cndmask_b32_e32 v0, v0, v5, vcc
	v_mul_lo_u32 v5, v3, v0
	v_add_u32_e32 v3, v5, v3
	v_cmp_ne_u32_e32 vcc, v4, v3
	s_and_saveexec_b64 s[2:3], vcc
	s_xor_b64 s[10:11], exec, s[2:3]
	s_cbranch_execz .LBB0_267
	v_readlane_b32 s2, v253, 63
	v_readlane_b32 s3, v254, 0
	s_waitcnt lgkmcnt(0)
	s_nop 3
	global_load_dword v2, v1, s[2:3] sc1
	s_waitcnt vmcnt(0)
	v_cmp_eq_u32_e32 vcc, v2, v0
	s_and_saveexec_b64 s[12:13], vcc
	s_cbranch_execz .LBB0_266
	s_mov_b32 s0, 1
	s_mov_b64 s[14:15], 0
	s_branch .LBB0_257

.LBB0_317:
	s_or_b64 exec, exec, s[8:9]
	v_cvt_f32_u32_e32 v5, v3
	s_waitcnt vmcnt(0)
	v_readfirstlane_b32 s0, v4
	v_sub_u32_e32 v4, 0, v3
	v_rcp_iflag_f32_e32 v5, v5
	v_add_u32_e32 v6, s0, v0
	v_mul_f32_e32 v5, 0x4f7ffffe, v5
	v_cvt_u32_f32_e32 v5, v5
	v_mul_lo_u32 v0, v4, v5
	v_mul_hi_u32 v0, v5, v0
	v_add_u32_e32 v0, v5, v0
	v_mul_hi_u32 v0, v6, v0
	v_mul_lo_u32 v4, v0, v3
	v_sub_u32_e32 v4, v6, v4
	v_add_u32_e32 v5, 1, v0
	v_cmp_ge_u32_e32 vcc, v4, v3
	s_nop 1
	v_cndmask_b32_e32 v0, v0, v5, vcc
	v_sub_u32_e32 v5, v4, v3
	v_cndmask_b32_e32 v4, v4, v5, vcc
	v_add_u32_e32 v5, 1, v0
	v_cmp_ge_u32_e32 vcc, v4, v3
	v_add_u32_e32 v4, 1, v6
	s_nop 0
	v_cndmask_b32_e32 v0, v0, v5, vcc
	v_mul_lo_u32 v5, v3, v0
	v_add_u32_e32 v3, v5, v3
	v_cmp_ne_u32_e32 vcc, v4, v3
	s_and_saveexec_b64 s[2:3], vcc
	s_xor_b64 s[8:9], exec, s[2:3]
	s_cbranch_execz .LBB0_331
	v_readlane_b32 s2, v253, 63
	v_readlane_b32 s3, v254, 0
	s_waitcnt lgkmcnt(0)
	s_nop 3
	global_load_dword v2, v1, s[2:3] sc1
	s_waitcnt vmcnt(0)
	v_cmp_eq_u32_e32 vcc, v2, v0
	s_and_saveexec_b64 s[10:11], vcc
	s_cbranch_execz .LBB0_330
	s_mov_b32 s0, 1
	s_mov_b64 s[12:13], 0
	s_branch .LBB0_321

.LBB0_648:
	s_or_b64 exec, exec, s[6:7]
	v_cvt_f32_u32_e32 v5, v3
	s_waitcnt vmcnt(0)
	v_readfirstlane_b32 s0, v4
	v_sub_u32_e32 v4, 0, v3
	v_rcp_iflag_f32_e32 v5, v5
	v_add_u32_e32 v6, s0, v0
	v_mul_f32_e32 v5, 0x4f7ffffe, v5
	v_cvt_u32_f32_e32 v5, v5
	v_mul_lo_u32 v0, v4, v5
	v_mul_hi_u32 v0, v5, v0
	v_add_u32_e32 v0, v5, v0
	v_mul_hi_u32 v0, v6, v0
	v_mul_lo_u32 v4, v0, v3
	v_sub_u32_e32 v4, v6, v4
	v_add_u32_e32 v5, 1, v0
	v_cmp_ge_u32_e32 vcc, v4, v3
	s_nop 1
	v_cndmask_b32_e32 v0, v0, v5, vcc
	v_sub_u32_e32 v5, v4, v3
	v_cndmask_b32_e32 v4, v4, v5, vcc
	v_add_u32_e32 v5, 1, v0
	v_cmp_ge_u32_e32 vcc, v4, v3
	v_add_u32_e32 v4, 1, v6
	s_nop 0
	v_cndmask_b32_e32 v0, v0, v5, vcc
	v_mul_lo_u32 v5, v3, v0
	v_add_u32_e32 v3, v5, v3
	v_cmp_ne_u32_e32 vcc, v4, v3
	s_and_saveexec_b64 s[2:3], vcc
	s_xor_b64 s[6:7], exec, s[2:3]
	s_cbranch_execz .LBB0_662
	v_readlane_b32 s2, v253, 63
	v_readlane_b32 s3, v254, 0
	s_waitcnt lgkmcnt(0)
	s_nop 3
	global_load_dword v2, v1, s[2:3] sc1
	s_waitcnt vmcnt(0)
	v_cmp_eq_u32_e32 vcc, v2, v0
	s_and_saveexec_b64 s[8:9], vcc
	s_cbranch_execz .LBB0_661
	s_mov_b32 s0, 1
	s_mov_b64 s[10:11], 0
	s_branch .LBB0_652

.LBB0_905:
	s_or_b64 exec, exec, s[6:7]
	v_cvt_f32_u32_e32 v5, v3
	s_waitcnt vmcnt(0)
	v_readfirstlane_b32 s0, v4
	v_sub_u32_e32 v4, 0, v3
	v_rcp_iflag_f32_e32 v5, v5
	v_add_u32_e32 v6, s0, v0
	v_mul_f32_e32 v5, 0x4f7ffffe, v5
	v_cvt_u32_f32_e32 v5, v5
	v_mul_lo_u32 v0, v4, v5
	v_mul_hi_u32 v0, v5, v0
	v_add_u32_e32 v0, v5, v0
	v_mul_hi_u32 v0, v6, v0
	v_mul_lo_u32 v4, v0, v3
	v_sub_u32_e32 v4, v6, v4
	v_add_u32_e32 v5, 1, v0
	v_cmp_ge_u32_e32 vcc, v4, v3
	s_nop 1
	v_cndmask_b32_e32 v0, v0, v5, vcc
	v_sub_u32_e32 v5, v4, v3
	v_cndmask_b32_e32 v4, v4, v5, vcc
	v_add_u32_e32 v5, 1, v0
	v_cmp_ge_u32_e32 vcc, v4, v3
	v_add_u32_e32 v4, 1, v6
	s_nop 0
	v_cndmask_b32_e32 v0, v0, v5, vcc
	v_mul_lo_u32 v5, v3, v0
	v_add_u32_e32 v3, v5, v3
	v_cmp_ne_u32_e32 vcc, v4, v3
	s_and_saveexec_b64 s[2:3], vcc
	s_xor_b64 s[6:7], exec, s[2:3]
	s_cbranch_execz .LBB0_919
	v_readlane_b32 s2, v253, 63
	v_readlane_b32 s3, v254, 0
	s_waitcnt lgkmcnt(0)
	s_nop 3
	global_load_dword v2, v1, s[2:3] sc1
	s_waitcnt vmcnt(0)
	v_cmp_eq_u32_e32 vcc, v2, v0
	s_and_saveexec_b64 s[10:11], vcc
	s_cbranch_execz .LBB0_918
	s_mov_b32 s0, 1
	s_mov_b64 s[12:13], 0
	s_branch .LBB0_909
